# P0a->P0b seam relaxed: only the 32 K/V-GEMM workgroups wait (acquire); conversion workgroups just arrive (hierarchical release kept)
# speedup vs baseline: 1.0091x; 1.0071x over previous
; __device__ __forceinline__ unsigned xb_ld(unsigned* p)              { return __hip_atomic_load(p, __ATOMIC_RELAXED, __HIP_MEMORY_SCOPE_AGENT); }
; __device__ __forceinline__ unsigned xb_add(unsigned* p, unsigned v) { return __hip_atomic_fetch_add(p, v, __ATOMIC_RELAXED, __HIP_MEMORY_SCOPE_AGENT); }
; #define XB_SPIN(cond, bar) do { unsigned _sp = 0; while (cond) { __builtin_amdgcn_s_sleep(1); \
;     if ((++_sp & 255u) == 0u) { if (xb_ld(&(bar)[XB_TMO])) break; if (_sp > XB_SPIN_CAP) { atomicAdd(&(bar)[XB_TMO], 1u); break; } } } } while (0)
; __device__ __forceinline__ void xcd_barrier(const XcdBarrier& b) {
;     ...
;         const unsigned old = xb_add(&bar[XB_XSUB(b.x)], 1u);
;         const unsigned gen = old / nloc;
;         if (old + 1u == (gen + 1u) * nloc) {
;             __builtin_amdgcn_fence(__ATOMIC_RELEASE, "agent");
;             asm volatile("s_waitcnt vmcnt(0)" ::: "memory");
;             const unsigned og = xb_add(&bar[XB_TOP], 1u);
;             const unsigned tg = og / nx;
;             if (og + 1u == (tg + 1u) * nx) xb_add(&bar[XB_TOPGEN], 1u);
;             else XB_SPIN(xb_ld(&bar[XB_TOPGEN]) == tg, bar);
;             __builtin_amdgcn_fence(__ATOMIC_ACQUIRE, "agent");
;             xb_add(&bar[XB_XGEN(b.x)], 1u);
;             asm volatile("s_waitcnt vmcnt(0)" ::: "memory");
;         } else {
;             XB_SPIN(xb_ld(&bar[XB_XGEN(b.x)]) == gen, bar);
;             __builtin_amdgcn_fence(__ATOMIC_ACQUIRE, "agent");
;             asm volatile("s_waitcnt vmcnt(0)" ::: "memory");
;         }
.LBB0_42:
	s_lshl_b32 s4, s84, 8
	s_add_u32 s4, s22, s4
	s_addc_u32 s5, s23, 0
	v_mov_b32_e32 v2, 0x1000
	v_mov_b32_e32 v4, 1
	global_atomic_add v4, v2, v4, s[4:5] offset:1024 sc0
	v_cvt_f32_u32_e32 v2, v3
	v_sub_u32_e32 v5, 0, v3
	v_rcp_iflag_f32_e32 v2, v2
	s_nop 0
	v_mul_f32_e32 v2, 0x4f7ffffe, v2
	v_cvt_u32_f32_e32 v2, v2
	v_mul_lo_u32 v5, v5, v2
	v_mul_hi_u32 v5, v2, v5
	v_add_u32_e32 v2, v2, v5
	s_waitcnt vmcnt(0)
	v_mul_hi_u32 v2, v4, v2
	v_mul_lo_u32 v5, v2, v3
	v_sub_u32_e32 v5, v4, v5
	v_add_u32_e32 v6, 1, v2
	v_cmp_ge_u32_e32 vcc, v5, v3
	v_add_u32_e32 v4, 1, v4
	s_nop 0
	v_cndmask_b32_e32 v2, v2, v6, vcc
	v_sub_u32_e32 v6, v5, v3
	v_cndmask_b32_e32 v5, v5, v6, vcc
	v_add_u32_e32 v6, 1, v2
	v_cmp_ge_u32_e32 vcc, v5, v3
	s_nop 1
	v_cndmask_b32_e32 v2, v2, v6, vcc
	v_mul_lo_u32 v5, v3, v2
	v_add_u32_e32 v3, v5, v3
	v_cmp_ne_u32_e32 vcc, v4, v3
	s_and_saveexec_b64 s[6:7], vcc
	s_xor_b64 s[6:7], exec, s[6:7]
	s_cbranch_execz .LBB0_56
	s_cmp_gt_i32 s2, 31
	s_cbranch_scc1 .LBB0_56
	s_waitcnt lgkmcnt(0)
	v_mov_b32_e32 v1, 0x3500
	global_load_dword v1, v1, s[22:23] sc1
	s_add_u32 s14, s22, 0x3500
	s_addc_u32 s15, s23, 0
	s_waitcnt vmcnt(0)
	v_cmp_eq_u32_e32 vcc, v1, v2
	s_and_saveexec_b64 s[10:11], vcc
	s_cbranch_execz .LBB0_55
	s_add_u32 s12, s24, 0x3e00200
	s_addc_u32 s13, s25, 0
	s_mov_b32 s36, 1
	s_mov_b64 s[16:17], 0
	v_mov_b32_e32 v1, 0
	s_branch .LBB0_46

; __device__ __forceinline__ unsigned xb_ld(unsigned* p)              { return __hip_atomic_load(p, __ATOMIC_RELAXED, __HIP_MEMORY_SCOPE_AGENT); }
; __device__ __forceinline__ unsigned xb_add(unsigned* p, unsigned v) { return __hip_atomic_fetch_add(p, v, __ATOMIC_RELAXED, __HIP_MEMORY_SCOPE_AGENT); }
; #define XB_SPIN(cond, bar) do { unsigned _sp = 0; while (cond) { __builtin_amdgcn_s_sleep(1); \
;     if ((++_sp & 255u) == 0u) { if (xb_ld(&(bar)[XB_TMO])) break; if (_sp > XB_SPIN_CAP) { atomicAdd(&(bar)[XB_TMO], 1u); break; } } } } while (0)
; __device__ __forceinline__ void xcd_barrier(const XcdBarrier& b) {
;     ...
;         const unsigned old = xb_add(&bar[XB_XSUB(b.x)], 1u);
;         const unsigned gen = old / nloc;
;         if (old + 1u == (gen + 1u) * nloc) {
;             __builtin_amdgcn_fence(__ATOMIC_RELEASE, "agent");
;             asm volatile("s_waitcnt vmcnt(0)" ::: "memory");
;             const unsigned og = xb_add(&bar[XB_TOP], 1u);
;             const unsigned tg = og / nx;
;             if (og + 1u == (tg + 1u) * nx) xb_add(&bar[XB_TOPGEN], 1u);
;             else XB_SPIN(xb_ld(&bar[XB_TOPGEN]) == tg, bar);
;             __builtin_amdgcn_fence(__ATOMIC_ACQUIRE, "agent");
;             xb_add(&bar[XB_XGEN(b.x)], 1u);
;             asm volatile("s_waitcnt vmcnt(0)" ::: "memory");
.LBB0_59:
	s_or_b64 exec, exec, s[10:11]
	v_cvt_f32_u32_e32 v4, v1
	s_waitcnt vmcnt(0)
	v_readfirstlane_b32 s6, v3
	s_add_u32 s10, s24, 0x3e03500
	s_addc_u32 s11, s25, 0
	v_rcp_iflag_f32_e32 v4, v4
	v_add_u32_e32 v2, s6, v2
	v_add_u32_e32 v5, 1, v2
	s_mov_b64 s[12:13], -1
	v_mul_f32_e32 v3, 0x4f7ffffe, v4
	v_cvt_u32_f32_e32 v3, v3
	v_sub_u32_e32 v4, 0, v1
	v_mul_lo_u32 v4, v4, v3
	v_mul_hi_u32 v4, v3, v4
	v_add_u32_e32 v3, v3, v4
	v_mul_hi_u32 v3, v2, v3
	v_mul_lo_u32 v4, v3, v1
	v_sub_u32_e32 v2, v2, v4
	v_add_u32_e32 v6, 1, v3
	v_cmp_ge_u32_e32 vcc, v2, v1
	v_sub_u32_e32 v4, v2, v1
	s_nop 0
	v_cndmask_b32_e32 v3, v3, v6, vcc
	v_cndmask_b32_e32 v2, v2, v4, vcc
	v_add_u32_e32 v4, 1, v3
	v_cmp_ge_u32_e32 vcc, v2, v1
	s_nop 1
	v_cndmask_b32_e32 v4, v3, v4, vcc
	v_mul_lo_u32 v2, v1, v4
	v_add_u32_e32 v1, v2, v1
	v_cmp_ne_u32_e32 vcc, v5, v1
	v_mov_b64_e32 v[2:3], s[10:11]
	s_and_saveexec_b64 s[6:7], vcc
	s_cbranch_execz .LBB0_71
	s_cmp_gt_i32 s2, 31
	s_cbranch_scc0 .Lseam0_ldr_wait
	s_mov_b64 s[12:13], 0
	s_branch .LBB0_71
.Lseam0_ldr_wait:
	v_mov_b32_e32 v1, 0
	global_load_dword v2, v1, s[10:11] sc1
	s_mov_b64 s[16:17], 0
	s_waitcnt vmcnt(0)
	v_cmp_eq_u32_e32 vcc, v2, v4
	s_and_saveexec_b64 s[14:15], vcc
	s_cbranch_execz .LBB0_70
	s_add_u32 s12, s24, 0x3e00200
	s_addc_u32 s13, s25, 0
	s_mov_b32 s36, 1
	s_branch .LBB0_63

; __global__ void __launch_bounds__(NTHR, 2) mk_fwd(Args a) {
;     ...
;             const int gw = (bx - 32) * NWAVES + wave, NGW = (G - 32) * NWAVES;
;             for (int it = gw; it < 3584 + 1536; it += NGW) {
;                 if (it < 3584) p0_transpose_item(w_in, 2048, INW, WinT, nullptr, scr, it, lane, 2);
;                 else p0_transpose_item(w_out, MIXW, DMODEL, WoutT, branch_norm, scr, it - 3584, lane, 2);
;             }
;             for (int p = gw; p < NTOK / 2; p += NGW) rms_rows_to_bf16<2>(x, norm_pre, Hb, 0, 2 * p, 1, NTOK, lane);
.LBB0_116:
	s_cmp_lg_u32 s33, 0
	s_cbranch_scc1 .Lp0b_chk_done
	v_mov_b32_e32 v125, 0x3500
	s_mov_b32 s0, 0
.Lp0b_chk:
	global_load_dword v126, v125, s[22:23] sc1
	s_waitcnt vmcnt(0)
	v_readfirstlane_b32 s1, v126
	s_nop 3
	s_cmp_lg_u32 s1, 0
	s_cbranch_scc1 .Lp0b_chk_done
	s_sleep 1
	s_add_i32 s0, s0, 1
	s_cmp_lt_u32 s0, 0x8000
	s_cbranch_scc1 .Lp0b_chk
